# V^T epilogue: dilation-16 scatter if-converted (4 full-exec dword stores per 16-row group instead of 6 exec-masked + 1)
# speedup vs baseline: 1.0038x; 1.0000x over previous
.LBB0_223:
	s_or_b64 exec, exec, s[12:13]
	v_cndmask_b32_e64 v136, v136, v138, s[6:7]
	v_xor_b32_e32 v138, 32, v185
	v_cmp_lt_i32_e32 vcc, v138, v195
	v_cndmask_b32_e64 v137, v137, v139, s[6:7]
	s_lshr_b32 s36, s33, 3
	v_cndmask_b32_e32 v138, v185, v138, vcc
	v_lshlrev_b32_e32 v138, 2, v138
	ds_bpermute_b32 v143, v138, v136
	ds_bpermute_b32 v142, v138, v137
	v_lshl_add_u64 v[136:137], v[170:171], 1, v[156:157]
	v_lshl_add_u64 v[176:177], v[176:177], 0, v[178:179]
	v_lshl_add_u64 v[136:137], v[136:137], 0, s[36:37]
	global_store_dwordx2 v[176:177], v[140:141], off
	s_waitcnt lgkmcnt(0)
	v_and_or_b32 v232, v143, s62, v194
	v_or_b32_sdwa v233, v143, v191 dst_sel:DWORD dst_unused:UNUSED_PAD src0_sel:WORD_1 src1_sel:DWORD
	v_and_or_b32 v234, v142, s62, v192
	v_or_b32_sdwa v235, v142, v193 dst_sel:DWORD dst_unused:UNUSED_PAD src0_sel:WORD_1 src1_sel:DWORD
	v_lshl_or_b32 v236, v143, 16, v187
	v_and_or_b32 v237, v143, s63, v188
	v_lshl_or_b32 v238, v142, 16, v189
	v_and_or_b32 v239, v142, s63, v190
	v_mov_b32_e32 v240, 0x1000
	v_mov_b32_e32 v241, 0
	v_cndmask_b32_e64 v232, v236, v232, s[8:9]
	v_cndmask_b32_e64 v233, v237, v233, s[8:9]
	v_cndmask_b32_e64 v234, v238, v234, s[8:9]
	v_cndmask_b32_e64 v235, v239, v235, s[8:9]
	v_cndmask_b32_e64 v240, 0, v240, s[8:9]
	v_lshl_add_u64 v[136:137], v[136:137], 0, v[240:241]
	global_store_dword v[136:137], v232, off
	global_store_dword v[136:137], v233, off offset:1024
	global_store_dword v[136:137], v234, off offset:2048
	global_store_dword v[136:137], v235, off offset:3072

.LBB0_233:
	s_or_b64 exec, exec, s[76:77]
	v_cndmask_b32_e64 v128, v128, v130, s[6:7]
	v_xor_b32_e32 v130, 32, v185
	v_cmp_lt_i32_e32 vcc, v130, v187
	v_cndmask_b32_e64 v129, v129, v131, s[6:7]
	s_lshr_b32 s36, s34, 3
	v_cndmask_b32_e32 v130, v185, v130, vcc
	v_lshlrev_b32_e32 v130, 2, v130
	ds_bpermute_b32 v135, v130, v128
	ds_bpermute_b32 v134, v130, v129
	v_lshl_add_u64 v[128:129], v[170:171], 1, v[156:157]
	v_lshl_add_u64 v[136:137], v[138:139], 0, v[140:141]
	v_lshl_add_u64 v[128:129], v[128:129], 0, s[36:37]
	global_store_dwordx2 v[136:137], v[132:133], off
	s_waitcnt lgkmcnt(0)
	v_and_or_b32 v232, v135, s62, v179
	v_or_b32_sdwa v233, v135, v176 dst_sel:DWORD dst_unused:UNUSED_PAD src0_sel:WORD_1 src1_sel:DWORD
	v_and_or_b32 v234, v134, s62, v177
	v_or_b32_sdwa v235, v134, v178 dst_sel:DWORD dst_unused:UNUSED_PAD src0_sel:WORD_1 src1_sel:DWORD
	v_lshl_or_b32 v236, v135, 16, v142
	v_and_or_b32 v237, v135, s63, v143
	v_lshl_or_b32 v238, v134, 16, v174
	v_and_or_b32 v239, v134, s63, v175
	v_mov_b32_e32 v240, 0x1000
	v_mov_b32_e32 v241, 0
	v_cndmask_b32_e64 v232, v236, v232, s[8:9]
	v_cndmask_b32_e64 v233, v237, v233, s[8:9]
	v_cndmask_b32_e64 v234, v238, v234, s[8:9]
	v_cndmask_b32_e64 v235, v239, v235, s[8:9]
	v_cndmask_b32_e64 v240, 0, v240, s[8:9]
	v_lshl_add_u64 v[128:129], v[128:129], 0, v[240:241]
	global_store_dword v[128:129], v232, off
	global_store_dword v[128:129], v233, off offset:1024
	global_store_dword v[128:129], v234, off offset:2048
	global_store_dword v[128:129], v235, off offset:3072

.LBB0_243:
	s_or_b64 exec, exec, s[76:77]
	v_cndmask_b32_e64 v120, v120, v122, s[6:7]
	v_xor_b32_e32 v122, 32, v185
	v_cmp_lt_i32_e32 vcc, v122, v174
	v_cndmask_b32_e64 v121, v121, v123, s[6:7]
	s_lshr_b32 s36, s33, 3
	v_cndmask_b32_e32 v122, v185, v122, vcc
	v_lshlrev_b32_e32 v122, 2, v122
	ds_bpermute_b32 v133, v122, v120
	ds_bpermute_b32 v132, v122, v121
	v_lshl_add_u64 v[120:121], v[128:129], 1, v[156:157]
	v_lshl_add_u64 v[134:135], v[136:137], 0, v[138:139]
	v_lshl_add_u64 v[120:121], v[120:121], 0, s[36:37]
	global_store_dwordx2 v[134:135], v[126:127], off
	s_waitcnt lgkmcnt(0)
	v_and_or_b32 v232, v133, s62, v173
	v_or_b32_sdwa v233, v133, v170 dst_sel:DWORD dst_unused:UNUSED_PAD src0_sel:WORD_1 src1_sel:DWORD
	v_and_or_b32 v234, v132, s62, v171
	v_or_b32_sdwa v235, v132, v172 dst_sel:DWORD dst_unused:UNUSED_PAD src0_sel:WORD_1 src1_sel:DWORD
	v_lshl_or_b32 v236, v133, 16, v140
	v_and_or_b32 v237, v133, s63, v141
	v_lshl_or_b32 v238, v132, 16, v142
	v_and_or_b32 v239, v132, s63, v143
	v_mov_b32_e32 v240, 0x1000
	v_mov_b32_e32 v241, 0
	v_cndmask_b32_e64 v232, v236, v232, s[8:9]
	v_cndmask_b32_e64 v233, v237, v233, s[8:9]
	v_cndmask_b32_e64 v234, v238, v234, s[8:9]
	v_cndmask_b32_e64 v235, v239, v235, s[8:9]
	v_cndmask_b32_e64 v240, 0, v240, s[8:9]
	v_lshl_add_u64 v[120:121], v[120:121], 0, v[240:241]
	global_store_dword v[120:121], v232, off
	global_store_dword v[120:121], v233, off offset:1024
	global_store_dword v[120:121], v234, off offset:2048
	global_store_dword v[120:121], v235, off offset:3072

.LBB0_253:
	s_or_b64 exec, exec, s[76:77]
	v_cndmask_b32_e64 v112, v112, v114, s[6:7]
	v_xor_b32_e32 v114, 32, v185
	v_cmp_lt_i32_e32 vcc, v114, v136
	v_cndmask_b32_e64 v113, v113, v115, s[6:7]
	s_lshr_b32 s36, s34, 3
	v_cndmask_b32_e32 v114, v185, v114, vcc
	v_lshlrev_b32_e32 v114, 2, v114
	ds_bpermute_b32 v119, v114, v112
	ds_bpermute_b32 v118, v114, v113
	v_lshl_add_u64 v[112:113], v[128:129], 1, v[156:157]
	v_lshl_add_u64 v[120:121], v[122:123], 0, v[124:125]
	v_lshl_add_u64 v[112:113], v[112:113], 0, s[36:37]
	global_store_dwordx2 v[120:121], v[116:117], off
	s_waitcnt lgkmcnt(0)
	v_and_or_b32 v232, v119, s62, v135
	v_or_b32_sdwa v233, v119, v132 dst_sel:DWORD dst_unused:UNUSED_PAD src0_sel:WORD_1 src1_sel:DWORD
	v_and_or_b32 v234, v118, s62, v133
	v_or_b32_sdwa v235, v118, v134 dst_sel:DWORD dst_unused:UNUSED_PAD src0_sel:WORD_1 src1_sel:DWORD
	v_lshl_or_b32 v236, v119, 16, v126
	v_and_or_b32 v237, v119, s63, v127
	v_lshl_or_b32 v238, v118, 16, v130
	v_and_or_b32 v239, v118, s63, v131
	v_mov_b32_e32 v240, 0x1000
	v_mov_b32_e32 v241, 0
	v_cndmask_b32_e64 v232, v236, v232, s[8:9]
	v_cndmask_b32_e64 v233, v237, v233, s[8:9]
	v_cndmask_b32_e64 v234, v238, v234, s[8:9]
	v_cndmask_b32_e64 v235, v239, v235, s[8:9]
	v_cndmask_b32_e64 v240, 0, v240, s[8:9]
	v_lshl_add_u64 v[112:113], v[112:113], 0, v[240:241]
	global_store_dword v[112:113], v232, off
	global_store_dword v[112:113], v233, off offset:1024
	global_store_dword v[112:113], v234, off offset:2048
	global_store_dword v[112:113], v235, off offset:3072

.LBB0_263:
	s_or_b64 exec, exec, s[76:77]
	v_cndmask_b32_e64 v104, v104, v106, s[6:7]
	v_xor_b32_e32 v106, 32, v185
	v_cmp_lt_i32_e32 vcc, v106, v132
	v_cndmask_b32_e64 v105, v105, v107, s[6:7]
	s_lshr_b32 s36, s33, 3
	v_cndmask_b32_e32 v106, v185, v106, vcc
	v_lshlrev_b32_e32 v106, 2, v106
	ds_bpermute_b32 v117, v106, v104
	ds_bpermute_b32 v116, v106, v105
	v_lshl_add_u64 v[104:105], v[112:113], 1, v[156:157]
	v_lshl_add_u64 v[118:119], v[120:121], 0, v[122:123]
	v_lshl_add_u64 v[104:105], v[104:105], 0, s[36:37]
	global_store_dwordx2 v[118:119], v[110:111], off
	s_waitcnt lgkmcnt(0)
	v_and_or_b32 v232, v117, s62, v131
	v_or_b32_sdwa v233, v117, v128 dst_sel:DWORD dst_unused:UNUSED_PAD src0_sel:WORD_1 src1_sel:DWORD
	v_and_or_b32 v234, v116, s62, v129
	v_or_b32_sdwa v235, v116, v130 dst_sel:DWORD dst_unused:UNUSED_PAD src0_sel:WORD_1 src1_sel:DWORD
	v_lshl_or_b32 v236, v117, 16, v124
	v_and_or_b32 v237, v117, s63, v125
	v_lshl_or_b32 v238, v116, 16, v126
	v_and_or_b32 v239, v116, s63, v127
	v_mov_b32_e32 v240, 0x1000
	v_mov_b32_e32 v241, 0
	v_cndmask_b32_e64 v232, v236, v232, s[8:9]
	v_cndmask_b32_e64 v233, v237, v233, s[8:9]
	v_cndmask_b32_e64 v234, v238, v234, s[8:9]
	v_cndmask_b32_e64 v235, v239, v235, s[8:9]
	v_cndmask_b32_e64 v240, 0, v240, s[8:9]
	v_lshl_add_u64 v[104:105], v[104:105], 0, v[240:241]
	global_store_dword v[104:105], v232, off
	global_store_dword v[104:105], v233, off offset:1024
	global_store_dword v[104:105], v234, off offset:2048
	global_store_dword v[104:105], v235, off offset:3072

.LBB0_273:
	s_or_b64 exec, exec, s[76:77]
	v_cndmask_b32_e64 v96, v96, v98, s[6:7]
	v_xor_b32_e32 v98, 32, v185
	v_cmp_lt_i32_e32 vcc, v98, v120
	v_cndmask_b32_e64 v97, v97, v99, s[6:7]
	s_lshr_b32 s36, s34, 3
	v_cndmask_b32_e32 v98, v185, v98, vcc
	v_lshlrev_b32_e32 v98, 2, v98
	ds_bpermute_b32 v103, v98, v96
	ds_bpermute_b32 v102, v98, v97
	v_lshl_add_u64 v[96:97], v[112:113], 1, v[156:157]
	v_lshl_add_u64 v[104:105], v[106:107], 0, v[108:109]
	v_lshl_add_u64 v[96:97], v[96:97], 0, s[36:37]
	global_store_dwordx2 v[104:105], v[100:101], off
	s_waitcnt lgkmcnt(0)
	v_and_or_b32 v232, v103, s62, v119
	v_or_b32_sdwa v233, v103, v116 dst_sel:DWORD dst_unused:UNUSED_PAD src0_sel:WORD_1 src1_sel:DWORD
	v_and_or_b32 v234, v102, s62, v117
	v_or_b32_sdwa v235, v102, v118 dst_sel:DWORD dst_unused:UNUSED_PAD src0_sel:WORD_1 src1_sel:DWORD
	v_lshl_or_b32 v236, v103, 16, v110
	v_and_or_b32 v237, v103, s63, v111
	v_lshl_or_b32 v238, v102, 16, v114
	v_and_or_b32 v239, v102, s63, v115
	v_mov_b32_e32 v240, 0x1000
	v_mov_b32_e32 v241, 0
	v_cndmask_b32_e64 v232, v236, v232, s[8:9]
	v_cndmask_b32_e64 v233, v237, v233, s[8:9]
	v_cndmask_b32_e64 v234, v238, v234, s[8:9]
	v_cndmask_b32_e64 v235, v239, v235, s[8:9]
	v_cndmask_b32_e64 v240, 0, v240, s[8:9]
	v_lshl_add_u64 v[96:97], v[96:97], 0, v[240:241]
	global_store_dword v[96:97], v232, off
	global_store_dword v[96:97], v233, off offset:1024
	global_store_dword v[96:97], v234, off offset:2048
	global_store_dword v[96:97], v235, off offset:3072

.LBB0_283:
	s_or_b64 exec, exec, s[76:77]
	v_cndmask_b32_e64 v88, v88, v90, s[6:7]
	v_xor_b32_e32 v90, 32, v185
	v_cmp_lt_i32_e32 vcc, v90, v116
	v_cndmask_b32_e64 v89, v89, v91, s[6:7]
	s_lshr_b32 s36, s33, 3
	v_cndmask_b32_e32 v90, v185, v90, vcc
	v_lshlrev_b32_e32 v90, 2, v90
	ds_bpermute_b32 v101, v90, v88
	ds_bpermute_b32 v100, v90, v89
	v_lshl_add_u64 v[88:89], v[96:97], 1, v[156:157]
	v_lshl_add_u64 v[102:103], v[104:105], 0, v[106:107]
	v_lshl_add_u64 v[88:89], v[88:89], 0, s[36:37]
	global_store_dwordx2 v[102:103], v[94:95], off
	s_waitcnt lgkmcnt(0)
	v_and_or_b32 v232, v101, s62, v115
	v_or_b32_sdwa v233, v101, v112 dst_sel:DWORD dst_unused:UNUSED_PAD src0_sel:WORD_1 src1_sel:DWORD
	v_and_or_b32 v234, v100, s62, v113
	v_or_b32_sdwa v235, v100, v114 dst_sel:DWORD dst_unused:UNUSED_PAD src0_sel:WORD_1 src1_sel:DWORD
	v_lshl_or_b32 v236, v101, 16, v108
	v_and_or_b32 v237, v101, s63, v109
	v_lshl_or_b32 v238, v100, 16, v110
	v_and_or_b32 v239, v100, s63, v111
	v_mov_b32_e32 v240, 0x1000
	v_mov_b32_e32 v241, 0
	v_cndmask_b32_e64 v232, v236, v232, s[8:9]
	v_cndmask_b32_e64 v233, v237, v233, s[8:9]
	v_cndmask_b32_e64 v234, v238, v234, s[8:9]
	v_cndmask_b32_e64 v235, v239, v235, s[8:9]
	v_cndmask_b32_e64 v240, 0, v240, s[8:9]
	v_lshl_add_u64 v[88:89], v[88:89], 0, v[240:241]
	global_store_dword v[88:89], v232, off
	global_store_dword v[88:89], v233, off offset:1024
	global_store_dword v[88:89], v234, off offset:2048
	global_store_dword v[88:89], v235, off offset:3072

.LBB0_293:
	s_or_b64 exec, exec, s[76:77]
	v_cndmask_b32_e64 v80, v80, v82, s[6:7]
	v_xor_b32_e32 v82, 32, v185
	v_cmp_lt_i32_e32 vcc, v82, v104
	v_cndmask_b32_e64 v81, v81, v83, s[6:7]
	s_lshr_b32 s36, s34, 3
	v_cndmask_b32_e32 v82, v185, v82, vcc
	v_lshlrev_b32_e32 v82, 2, v82
	ds_bpermute_b32 v87, v82, v80
	ds_bpermute_b32 v86, v82, v81
	v_lshl_add_u64 v[80:81], v[96:97], 1, v[156:157]
	v_lshl_add_u64 v[88:89], v[90:91], 0, v[92:93]
	v_lshl_add_u64 v[80:81], v[80:81], 0, s[36:37]
	global_store_dwordx2 v[88:89], v[84:85], off
	s_waitcnt lgkmcnt(0)
	v_and_or_b32 v232, v87, s62, v103
	v_or_b32_sdwa v233, v87, v100 dst_sel:DWORD dst_unused:UNUSED_PAD src0_sel:WORD_1 src1_sel:DWORD
	v_and_or_b32 v234, v86, s62, v101
	v_or_b32_sdwa v235, v86, v102 dst_sel:DWORD dst_unused:UNUSED_PAD src0_sel:WORD_1 src1_sel:DWORD
	v_lshl_or_b32 v236, v87, 16, v94
	v_and_or_b32 v237, v87, s63, v95
	v_lshl_or_b32 v238, v86, 16, v98
	v_and_or_b32 v239, v86, s63, v99
	v_mov_b32_e32 v240, 0x1000
	v_mov_b32_e32 v241, 0
	v_cndmask_b32_e64 v232, v236, v232, s[8:9]
	v_cndmask_b32_e64 v233, v237, v233, s[8:9]
	v_cndmask_b32_e64 v234, v238, v234, s[8:9]
	v_cndmask_b32_e64 v235, v239, v235, s[8:9]
	v_cndmask_b32_e64 v240, 0, v240, s[8:9]
	v_lshl_add_u64 v[80:81], v[80:81], 0, v[240:241]
	global_store_dword v[80:81], v232, off
	global_store_dword v[80:81], v233, off offset:1024
	global_store_dword v[80:81], v234, off offset:2048
	global_store_dword v[80:81], v235, off offset:3072

.LBB0_303:
	s_or_b64 exec, exec, s[76:77]
	v_cndmask_b32_e64 v72, v72, v74, s[6:7]
	v_xor_b32_e32 v74, 32, v185
	v_cmp_lt_i32_e32 vcc, v74, v100
	v_cndmask_b32_e64 v73, v73, v75, s[6:7]
	s_lshr_b32 s36, s33, 3
	v_cndmask_b32_e32 v74, v185, v74, vcc
	v_lshlrev_b32_e32 v74, 2, v74
	ds_bpermute_b32 v85, v74, v72
	ds_bpermute_b32 v84, v74, v73
	v_lshl_add_u64 v[72:73], v[80:81], 1, v[156:157]
	v_lshl_add_u64 v[86:87], v[88:89], 0, v[90:91]
	v_lshl_add_u64 v[72:73], v[72:73], 0, s[36:37]
	global_store_dwordx2 v[86:87], v[78:79], off
	s_waitcnt lgkmcnt(0)
	v_and_or_b32 v232, v85, s62, v99
	v_or_b32_sdwa v233, v85, v96 dst_sel:DWORD dst_unused:UNUSED_PAD src0_sel:WORD_1 src1_sel:DWORD
	v_and_or_b32 v234, v84, s62, v97
	v_or_b32_sdwa v235, v84, v98 dst_sel:DWORD dst_unused:UNUSED_PAD src0_sel:WORD_1 src1_sel:DWORD
	v_lshl_or_b32 v236, v85, 16, v92
	v_and_or_b32 v237, v85, s63, v93
	v_lshl_or_b32 v238, v84, 16, v94
	v_and_or_b32 v239, v84, s63, v95
	v_mov_b32_e32 v240, 0x1000
	v_mov_b32_e32 v241, 0
	v_cndmask_b32_e64 v232, v236, v232, s[8:9]
	v_cndmask_b32_e64 v233, v237, v233, s[8:9]
	v_cndmask_b32_e64 v234, v238, v234, s[8:9]
	v_cndmask_b32_e64 v235, v239, v235, s[8:9]
	v_cndmask_b32_e64 v240, 0, v240, s[8:9]
	v_lshl_add_u64 v[72:73], v[72:73], 0, v[240:241]
	global_store_dword v[72:73], v232, off
	global_store_dword v[72:73], v233, off offset:1024
	global_store_dword v[72:73], v234, off offset:2048
	global_store_dword v[72:73], v235, off offset:3072

.LBB0_313:
	s_or_b64 exec, exec, s[76:77]
	v_cndmask_b32_e64 v64, v64, v66, s[6:7]
	v_xor_b32_e32 v66, 32, v185
	v_cmp_lt_i32_e32 vcc, v66, v88
	v_cndmask_b32_e64 v65, v65, v67, s[6:7]
	s_lshr_b32 s36, s34, 3
	v_cndmask_b32_e32 v66, v185, v66, vcc
	v_lshlrev_b32_e32 v66, 2, v66
	ds_bpermute_b32 v71, v66, v64
	ds_bpermute_b32 v70, v66, v65
	v_lshl_add_u64 v[64:65], v[80:81], 1, v[156:157]
	v_lshl_add_u64 v[72:73], v[74:75], 0, v[76:77]
	v_lshl_add_u64 v[64:65], v[64:65], 0, s[36:37]
	global_store_dwordx2 v[72:73], v[68:69], off
	s_waitcnt lgkmcnt(0)
	v_and_or_b32 v232, v71, s62, v87
	v_or_b32_sdwa v233, v71, v84 dst_sel:DWORD dst_unused:UNUSED_PAD src0_sel:WORD_1 src1_sel:DWORD
	v_and_or_b32 v234, v70, s62, v85
	v_or_b32_sdwa v235, v70, v86 dst_sel:DWORD dst_unused:UNUSED_PAD src0_sel:WORD_1 src1_sel:DWORD
	v_lshl_or_b32 v236, v71, 16, v78
	v_and_or_b32 v237, v71, s63, v79
	v_lshl_or_b32 v238, v70, 16, v82
	v_and_or_b32 v239, v70, s63, v83
	v_mov_b32_e32 v240, 0x1000
	v_mov_b32_e32 v241, 0
	v_cndmask_b32_e64 v232, v236, v232, s[8:9]
	v_cndmask_b32_e64 v233, v237, v233, s[8:9]
	v_cndmask_b32_e64 v234, v238, v234, s[8:9]
	v_cndmask_b32_e64 v235, v239, v235, s[8:9]
	v_cndmask_b32_e64 v240, 0, v240, s[8:9]
	v_lshl_add_u64 v[64:65], v[64:65], 0, v[240:241]
	global_store_dword v[64:65], v232, off
	global_store_dword v[64:65], v233, off offset:1024
	global_store_dword v[64:65], v234, off offset:2048
	global_store_dword v[64:65], v235, off offset:3072

.LBB0_323:
	s_or_b64 exec, exec, s[76:77]
	v_cndmask_b32_e64 v56, v56, v58, s[6:7]
	v_xor_b32_e32 v58, 32, v185
	v_cmp_lt_i32_e32 vcc, v58, v84
	v_cndmask_b32_e64 v57, v57, v59, s[6:7]
	s_lshr_b32 s36, s33, 3
	v_cndmask_b32_e32 v58, v185, v58, vcc
	v_lshlrev_b32_e32 v58, 2, v58
	ds_bpermute_b32 v69, v58, v56
	ds_bpermute_b32 v68, v58, v57
	v_lshl_add_u64 v[56:57], v[64:65], 1, v[156:157]
	v_lshl_add_u64 v[70:71], v[72:73], 0, v[74:75]
	v_lshl_add_u64 v[56:57], v[56:57], 0, s[36:37]
	global_store_dwordx2 v[70:71], v[62:63], off
	s_waitcnt lgkmcnt(0)
	v_and_or_b32 v232, v69, s62, v83
	v_or_b32_sdwa v233, v69, v80 dst_sel:DWORD dst_unused:UNUSED_PAD src0_sel:WORD_1 src1_sel:DWORD
	v_and_or_b32 v234, v68, s62, v81
	v_or_b32_sdwa v235, v68, v82 dst_sel:DWORD dst_unused:UNUSED_PAD src0_sel:WORD_1 src1_sel:DWORD
	v_lshl_or_b32 v236, v69, 16, v76
	v_and_or_b32 v237, v69, s63, v77
	v_lshl_or_b32 v238, v68, 16, v78
	v_and_or_b32 v239, v68, s63, v79
	v_mov_b32_e32 v240, 0x1000
	v_mov_b32_e32 v241, 0
	v_cndmask_b32_e64 v232, v236, v232, s[8:9]
	v_cndmask_b32_e64 v233, v237, v233, s[8:9]
	v_cndmask_b32_e64 v234, v238, v234, s[8:9]
	v_cndmask_b32_e64 v235, v239, v235, s[8:9]
	v_cndmask_b32_e64 v240, 0, v240, s[8:9]
	v_lshl_add_u64 v[56:57], v[56:57], 0, v[240:241]
	global_store_dword v[56:57], v232, off
	global_store_dword v[56:57], v233, off offset:1024
	global_store_dword v[56:57], v234, off offset:2048
	global_store_dword v[56:57], v235, off offset:3072

.LBB0_333:
	s_or_b64 exec, exec, s[76:77]
	v_cndmask_b32_e64 v32, v32, v34, s[6:7]
	v_xor_b32_e32 v34, 32, v185
	v_cmp_lt_i32_e32 vcc, v34, v72
	v_cndmask_b32_e64 v33, v33, v35, s[6:7]
	s_lshr_b32 s36, s34, 3
	v_cndmask_b32_e32 v34, v185, v34, vcc
	v_lshlrev_b32_e32 v34, 2, v34
	ds_bpermute_b32 v39, v34, v32
	ds_bpermute_b32 v38, v34, v33
	v_lshl_add_u64 v[32:33], v[64:65], 1, v[156:157]
	v_lshl_add_u64 v[56:57], v[58:59], 0, v[60:61]
	v_lshl_add_u64 v[32:33], v[32:33], 0, s[36:37]
	global_store_dwordx2 v[56:57], v[36:37], off
	s_waitcnt lgkmcnt(0)
	v_and_or_b32 v232, v39, s62, v71
	v_or_b32_sdwa v233, v39, v68 dst_sel:DWORD dst_unused:UNUSED_PAD src0_sel:WORD_1 src1_sel:DWORD
	v_and_or_b32 v234, v38, s62, v69
	v_or_b32_sdwa v235, v38, v70 dst_sel:DWORD dst_unused:UNUSED_PAD src0_sel:WORD_1 src1_sel:DWORD
	v_lshl_or_b32 v236, v39, 16, v62
	v_and_or_b32 v237, v39, s63, v63
	v_lshl_or_b32 v238, v38, 16, v66
	v_and_or_b32 v239, v38, s63, v67
	v_mov_b32_e32 v240, 0x1000
	v_mov_b32_e32 v241, 0
	v_cndmask_b32_e64 v232, v236, v232, s[8:9]
	v_cndmask_b32_e64 v233, v237, v233, s[8:9]
	v_cndmask_b32_e64 v234, v238, v234, s[8:9]
	v_cndmask_b32_e64 v235, v239, v235, s[8:9]
	v_cndmask_b32_e64 v240, 0, v240, s[8:9]
	v_lshl_add_u64 v[32:33], v[32:33], 0, v[240:241]
	global_store_dword v[32:33], v232, off
	global_store_dword v[32:33], v233, off offset:1024
	global_store_dword v[32:33], v234, off offset:2048
	global_store_dword v[32:33], v235, off offset:3072

.LBB0_343:
	s_or_b64 exec, exec, s[76:77]
	v_cndmask_b32_e64 v24, v24, v26, s[6:7]
	v_xor_b32_e32 v26, 32, v185
	v_cmp_lt_i32_e32 vcc, v26, v68
	v_cndmask_b32_e64 v25, v25, v27, s[6:7]
	s_lshr_b32 s36, s33, 3
	v_cndmask_b32_e32 v26, v185, v26, vcc
	v_lshlrev_b32_e32 v26, 2, v26
	ds_bpermute_b32 v37, v26, v24
	ds_bpermute_b32 v36, v26, v25
	v_lshl_add_u64 v[24:25], v[32:33], 1, v[156:157]
	v_lshl_add_u64 v[38:39], v[56:57], 0, v[58:59]
	v_lshl_add_u64 v[24:25], v[24:25], 0, s[36:37]
	global_store_dwordx2 v[38:39], v[30:31], off
	s_waitcnt lgkmcnt(0)
	v_and_or_b32 v232, v37, s62, v67
	v_or_b32_sdwa v233, v37, v64 dst_sel:DWORD dst_unused:UNUSED_PAD src0_sel:WORD_1 src1_sel:DWORD
	v_and_or_b32 v234, v36, s62, v65
	v_or_b32_sdwa v235, v36, v66 dst_sel:DWORD dst_unused:UNUSED_PAD src0_sel:WORD_1 src1_sel:DWORD
	v_lshl_or_b32 v236, v37, 16, v60
	v_and_or_b32 v237, v37, s63, v61
	v_lshl_or_b32 v238, v36, 16, v62
	v_and_or_b32 v239, v36, s63, v63
	v_mov_b32_e32 v240, 0x1000
	v_mov_b32_e32 v241, 0
	v_cndmask_b32_e64 v232, v236, v232, s[8:9]
	v_cndmask_b32_e64 v233, v237, v233, s[8:9]
	v_cndmask_b32_e64 v234, v238, v234, s[8:9]
	v_cndmask_b32_e64 v235, v239, v235, s[8:9]
	v_cndmask_b32_e64 v240, 0, v240, s[8:9]
	v_lshl_add_u64 v[24:25], v[24:25], 0, v[240:241]
	global_store_dword v[24:25], v232, off
	global_store_dword v[24:25], v233, off offset:1024
	global_store_dword v[24:25], v234, off offset:2048
	global_store_dword v[24:25], v235, off offset:3072

.LBB0_353:
	s_or_b64 exec, exec, s[76:77]
	v_cndmask_b32_e64 v16, v16, v18, s[6:7]
	v_xor_b32_e32 v18, 32, v185
	v_cmp_lt_i32_e32 vcc, v18, v56
	v_cndmask_b32_e64 v17, v17, v19, s[6:7]
	s_lshr_b32 s36, s34, 3
	v_cndmask_b32_e32 v18, v185, v18, vcc
	v_lshlrev_b32_e32 v18, 2, v18
	ds_bpermute_b32 v23, v18, v16
	ds_bpermute_b32 v22, v18, v17
	v_lshl_add_u64 v[16:17], v[32:33], 1, v[156:157]
	v_lshl_add_u64 v[24:25], v[26:27], 0, v[28:29]
	v_lshl_add_u64 v[16:17], v[16:17], 0, s[36:37]
	global_store_dwordx2 v[24:25], v[20:21], off
	s_waitcnt lgkmcnt(0)
	v_and_or_b32 v232, v23, s62, v39
	v_or_b32_sdwa v233, v23, v36 dst_sel:DWORD dst_unused:UNUSED_PAD src0_sel:WORD_1 src1_sel:DWORD
	v_and_or_b32 v234, v22, s62, v37
	v_or_b32_sdwa v235, v22, v38 dst_sel:DWORD dst_unused:UNUSED_PAD src0_sel:WORD_1 src1_sel:DWORD
	v_lshl_or_b32 v236, v23, 16, v30
	v_and_or_b32 v237, v23, s63, v31
	v_lshl_or_b32 v238, v22, 16, v34
	v_and_or_b32 v239, v22, s63, v35
	v_mov_b32_e32 v240, 0x1000
	v_mov_b32_e32 v241, 0
	v_cndmask_b32_e64 v232, v236, v232, s[8:9]
	v_cndmask_b32_e64 v233, v237, v233, s[8:9]
	v_cndmask_b32_e64 v234, v238, v234, s[8:9]
	v_cndmask_b32_e64 v235, v239, v235, s[8:9]
	v_cndmask_b32_e64 v240, 0, v240, s[8:9]
	v_lshl_add_u64 v[16:17], v[16:17], 0, v[240:241]
	global_store_dword v[16:17], v232, off
	global_store_dword v[16:17], v233, off offset:1024
	global_store_dword v[16:17], v234, off offset:2048
	global_store_dword v[16:17], v235, off offset:3072

.LBB0_363:
	s_or_b64 exec, exec, s[74:75]
	v_cndmask_b32_e64 v8, v8, v10, s[6:7]
	v_xor_b32_e32 v10, 32, v185
	v_cmp_lt_i32_e32 vcc, v10, v36
	v_cndmask_b32_e64 v9, v9, v11, s[6:7]
	s_lshr_b32 s36, s33, 3
	v_cndmask_b32_e32 v10, v185, v10, vcc
	v_lshlrev_b32_e32 v10, 2, v10
	ds_bpermute_b32 v21, v10, v8
	ds_bpermute_b32 v20, v10, v9
	v_lshl_add_u64 v[8:9], v[16:17], 1, v[156:157]
	v_lshl_add_u64 v[22:23], v[24:25], 0, v[26:27]
	v_lshl_add_u64 v[8:9], v[8:9], 0, s[36:37]
	global_store_dwordx2 v[22:23], v[14:15], off
	s_waitcnt lgkmcnt(0)
	v_and_or_b32 v232, v21, s62, v35
	v_or_b32_sdwa v233, v21, v32 dst_sel:DWORD dst_unused:UNUSED_PAD src0_sel:WORD_1 src1_sel:DWORD
	v_and_or_b32 v234, v20, s62, v33
	v_or_b32_sdwa v235, v20, v34 dst_sel:DWORD dst_unused:UNUSED_PAD src0_sel:WORD_1 src1_sel:DWORD
	v_lshl_or_b32 v236, v21, 16, v28
	v_and_or_b32 v237, v21, s63, v29
	v_lshl_or_b32 v238, v20, 16, v30
	v_and_or_b32 v239, v20, s63, v31
	v_mov_b32_e32 v240, 0x1000
	v_mov_b32_e32 v241, 0
	v_cndmask_b32_e64 v232, v236, v232, s[8:9]
	v_cndmask_b32_e64 v233, v237, v233, s[8:9]
	v_cndmask_b32_e64 v234, v238, v234, s[8:9]
	v_cndmask_b32_e64 v235, v239, v235, s[8:9]
	v_cndmask_b32_e64 v240, 0, v240, s[8:9]
	v_lshl_add_u64 v[8:9], v[8:9], 0, v[240:241]
	global_store_dword v[8:9], v232, off
	global_store_dword v[8:9], v233, off offset:1024
	global_store_dword v[8:9], v234, off offset:2048
	global_store_dword v[8:9], v235, off offset:3072

.LBB0_373:
	s_or_b64 exec, exec, s[12:13]
	v_cndmask_b32_e64 v0, v0, v2, s[6:7]
	v_xor_b32_e32 v2, 32, v185
	v_cmp_lt_i32_e32 vcc, v2, v24
	v_cndmask_b32_e64 v1, v1, v3, s[6:7]
	s_lshr_b32 s36, s33, 3
	v_cndmask_b32_e32 v2, v185, v2, vcc
	v_lshlrev_b32_e32 v2, 2, v2
	ds_bpermute_b32 v7, v2, v0
	ds_bpermute_b32 v6, v2, v1
	v_lshl_add_u64 v[0:1], v[16:17], 1, v[156:157]
	v_lshl_add_u64 v[8:9], v[10:11], 0, v[12:13]
	v_lshl_add_u64 v[0:1], v[0:1], 0, s[36:37]
	global_store_dwordx2 v[8:9], v[4:5], off
	s_waitcnt lgkmcnt(0)
	v_and_or_b32 v232, v7, s62, v23
	v_or_b32_sdwa v233, v7, v20 dst_sel:DWORD dst_unused:UNUSED_PAD src0_sel:WORD_1 src1_sel:DWORD
	v_and_or_b32 v234, v6, s62, v21
	v_or_b32_sdwa v235, v6, v22 dst_sel:DWORD dst_unused:UNUSED_PAD src0_sel:WORD_1 src1_sel:DWORD
	v_lshl_or_b32 v236, v7, 16, v14
	v_and_or_b32 v237, v7, s63, v15
	v_lshl_or_b32 v238, v6, 16, v18
	v_and_or_b32 v239, v6, s63, v19
	v_mov_b32_e32 v240, 0x1000
	v_mov_b32_e32 v241, 0
	v_cndmask_b32_e64 v232, v236, v232, s[8:9]
	v_cndmask_b32_e64 v233, v237, v233, s[8:9]
	v_cndmask_b32_e64 v234, v238, v234, s[8:9]
	v_cndmask_b32_e64 v235, v239, v235, s[8:9]
	v_cndmask_b32_e64 v240, 0, v240, s[8:9]
	v_lshl_add_u64 v[0:1], v[0:1], 0, v[240:241]
	global_store_dword v[0:1], v232, off
	global_store_dword v[0:1], v233, off offset:1024
	global_store_dword v[0:1], v234, off offset:2048
	global_store_dword v[0:1], v235, off offset:3072
